# strategy 7: DPP (quad_perm/row_half_mirror/row_mirror) replaces 8 ds_bpermute round trips per conv P3 l2norm; same add order
# speedup vs baseline: 1.0026x; 1.0020x over previous
; #define LAS __attribute__((address_space(3)))
; __device__ __forceinline__ vu4 pack8(const float (&f)[8]) { vu4 w; w.x = pg8::cvt_pk_bf16(f[0], f[1]); w.y = pg8::cvt_pk_bf16(f[2], f[3]); w.z = pg8::cvt_pk_bf16(f[4], f[5]); w.w = pg8::cvt_pk_bf16(f[6], f[7]); return w; }
; __device__ __forceinline__ float silu_f(float x) { return x * __builtin_amdgcn_rcpf(1.0f + __expf(-x)); }
; __device__ __forceinline__ void ph_conv_inplace(lds_u8* lds, bf16_t* XT, const float* convw, const bf16_t* halo, int norm_mode) {
;     ...
;         for (int i = 0; i < 2; ++i) { const int r = (tid >> 4) + 32 * i; float acc[8];
; #pragma unroll
;             for (int j = 0; j < 8; ++j) acc[j] = 0.f;
; #pragma unroll
;             for (int tap = 0; tap < 5; ++tap) { float xv[8]; unpack8(*(const LAS vu4*)(raw + (r + tap) * 128 + g8 * 8), xv);
; #pragma unroll
;                 for (int j = 0; j < 8; ++j) acc[j] += cw[tap][j] * xv[j]; }
;             float ss = 0.f;
; #pragma unroll
;             for (int j = 0; j < 8; ++j) { acc[j] = silu_f(acc[j]); ss += acc[j] * acc[j]; }
;             if (norm_mode == 1 && cb < 32) { ss += __shfl_xor(ss, 1); ss += __shfl_xor(ss, 2); ss += __shfl_xor(ss, 4); ss += __shfl_xor(ss, 8);
;                 const float sc = rsqrtf(ss + EPSN) * (cb < 16 ? 0.08838834764831845f : 1.0f);
; #pragma unroll
;                 for (int j = 0; j < 8; ++j) acc[j] *= sc; }
;             outv[i] = pack8(acc); }
.LBB0_382:
	s_waitcnt lgkmcnt(0)
	s_barrier
	ds_read_b128 v[64:67], v77
	ds_read_b128 v[68:71], v77 offset:256
	ds_read_b128 v[84:87], v77 offset:512
	ds_read_b128 v[88:91], v77 offset:768
	ds_read_b128 v[92:95], v77 offset:1024
	s_add_i32 s23, s44, s46
	s_waitcnt lgkmcnt(4)
	v_lshlrev_b32_e32 v72, 16, v64
	v_and_b32_e32 v73, 0xffff0000, v64
	s_waitcnt lgkmcnt(3)
	v_lshlrev_b32_e32 v100, 16, v68
	v_and_b32_e32 v101, 0xffff0000, v68
	s_waitcnt lgkmcnt(2)
	v_lshlrev_b32_e32 v102, 16, v84
	v_and_b32_e32 v103, 0xffff0000, v84
	s_waitcnt lgkmcnt(1)
	v_lshlrev_b32_e32 v104, 16, v88
	v_and_b32_e32 v105, 0xffff0000, v88
	s_waitcnt lgkmcnt(0)
	v_lshlrev_b32_e32 v106, 16, v92
	v_and_b32_e32 v107, 0xffff0000, v92
	v_lshlrev_b32_e32 v74, 16, v71
	v_lshlrev_b32_e32 v64, 16, v65
	v_and_b32_e32 v65, 0xffff0000, v65
	v_lshlrev_b32_e32 v68, 16, v69
	v_and_b32_e32 v69, 0xffff0000, v69
	v_lshlrev_b32_e32 v75, 16, v87
	v_and_b32_e32 v96, 0xffff0000, v71
	v_lshlrev_b32_e32 v71, 16, v91
	v_and_b32_e32 v97, 0xffff0000, v87
	v_and_b32_e32 v99, 0xffff0000, v95
	v_and_b32_e32 v98, 0xffff0000, v91
	v_lshlrev_b32_e32 v83, 16, v95
	s_cmp_lt_i32 s23, 32
	s_cselect_b64 s[20:21], -1, 0
	s_cmp_lt_i32 s23, 16
	s_cselect_b64 vcc, -1, 0
	s_cmp_gt_i32 s23, 31
	v_cndmask_b32_e32 v82, 1.0, v80, vcc
	s_waitcnt vmcnt(11)
	v_pk_fma_f32 v[108:109], v[34:35], v[72:73], 0 op_sel_hi:[1,1,0]
	s_waitcnt vmcnt(10)
	v_pk_fma_f32 v[100:101], v[38:39], v[100:101], v[108:109]
	s_waitcnt vmcnt(9)
	v_mul_f32_e32 v84, v20, v74
	v_mov_b32_e32 v74, v21
	s_waitcnt vmcnt(8)
	v_pk_fma_f32 v[100:101], v[42:43], v[102:103], v[100:101]
	v_pk_fma_f32 v[64:65], v[36:37], v[64:65], 0 op_sel_hi:[1,1,0]
	s_waitcnt vmcnt(7)
	v_mul_f32_e32 v88, v24, v75
	v_pk_fma_f32 v[64:65], v[40:41], v[68:69], v[64:65]
	v_lshlrev_b32_e32 v68, 16, v85
	v_and_b32_e32 v69, 0xffff0000, v85
	v_pk_fma_f32 v[64:65], v[44:45], v[68:69], v[64:65]
	v_lshlrev_b32_e32 v68, 16, v89
	v_and_b32_e32 v69, 0xffff0000, v89
	s_waitcnt vmcnt(4)
	v_pk_fma_f32 v[100:101], v[50:51], v[104:105], v[100:101]
	v_pk_fma_f32 v[64:65], v[52:53], v[68:69], v[64:65]
	v_lshlrev_b32_e32 v68, 16, v93
	v_and_b32_e32 v69, 0xffff0000, v93
	v_mov_b32_e32 v75, v25
	s_waitcnt vmcnt(3)
	v_pk_fma_f32 v[100:101], v[46:47], v[106:107], v[100:101]
	v_pk_fma_f32 v[68:69], v[48:49], v[68:69], v[64:65]
	v_mul_f32_e32 v21, 0xbfb8aa3b, v100
	v_exp_f32_e32 v21, v21
	v_mul_f32_e32 v25, 0xbfb8aa3b, v101
	v_lshlrev_b32_e32 v64, 16, v66
	v_and_b32_e32 v65, 0xffff0000, v66
	v_add_f32_e32 v21, 1.0, v21
	v_exp_f32_e32 v25, v25
	v_rcp_f32_e32 v102, v21
	v_mul_f32_e32 v21, 0xbfb8aa3b, v68
	s_waitcnt vmcnt(2)
	v_pk_fma_f32 v[64:65], v[14:15], v[64:65], 0 op_sel_hi:[1,1,0]
	v_lshlrev_b32_e32 v106, 16, v70
	v_and_b32_e32 v107, 0xffff0000, v70
	v_mul_f32_e32 v92, v28, v71
	v_mov_b32_e32 v72, v29
	v_exp_f32_e32 v21, v21
	v_mul_f32_e32 v29, 0xbfb8aa3b, v69
	v_pk_fma_f32 v[64:65], v[18:19], v[106:107], v[64:65]
	v_lshlrev_b32_e32 v70, 16, v86
	v_and_b32_e32 v71, 0xffff0000, v86
	v_exp_f32_e32 v29, v29
	v_pk_fma_f32 v[64:65], v[22:23], v[70:71], v[64:65]
	v_lshlrev_b32_e32 v70, 16, v90
	v_and_b32_e32 v71, 0xffff0000, v90
	v_pk_fma_f32 v[64:65], v[26:27], v[70:71], v[64:65]
	v_lshlrev_b32_e32 v70, 16, v94
	v_and_b32_e32 v71, 0xffff0000, v94
	v_pk_mul_f32 v[96:97], v[74:75], v[96:97]
	v_add_f32_e32 v25, 1.0, v25
	v_pk_fma_f32 v[70:71], v[30:31], v[70:71], v[64:65]
	v_and_b32_e32 v65, 0xffff0000, v67
	v_lshlrev_b32_e32 v64, 16, v67
	v_mov_b32_e32 v73, v33
	v_rcp_f32_e32 v103, v25
	v_add_f32_e32 v21, 1.0, v21
	v_mul_f32_e32 v25, 0xbfb8aa3b, v70
	v_pk_fma_f32 v[64:65], v[16:17], v[64:65], 0 op_sel_hi:[1,1,0]
	v_mov_b32_e32 v85, v96
	v_pk_mul_f32 v[98:99], v[72:73], v[98:99]
	v_rcp_f32_e32 v104, v21
	v_add_f32_e32 v21, 1.0, v29
	v_exp_f32_e32 v25, v25
	v_mul_f32_e32 v29, 0xbfb8aa3b, v71
	v_pk_add_f32 v[64:65], v[64:65], v[84:85]
	v_mov_b32_e32 v89, v97
	v_exp_f32_e32 v29, v29
	v_pk_add_f32 v[64:65], v[64:65], v[88:89]
	v_mov_b32_e32 v93, v98
	v_mul_f32_e32 v110, v32, v83
	v_pk_add_f32 v[64:65], v[64:65], v[92:93]
	v_mov_b32_e32 v111, v99
	v_pk_add_f32 v[84:85], v[64:65], v[110:111]
	v_rcp_f32_e32 v105, v21
	v_add_f32_e32 v21, 1.0, v25
	v_mul_f32_e32 v25, 0xbfb8aa3b, v84
	v_rcp_f32_e32 v86, v21
	v_add_f32_e32 v21, 1.0, v29
	v_exp_f32_e32 v25, v25
	v_mul_f32_e32 v29, 0xbfb8aa3b, v85
	v_exp_f32_e32 v29, v29
	v_rcp_f32_e32 v87, v21
	v_add_f32_e32 v21, 1.0, v25
	v_rcp_f32_e32 v88, v21
	v_add_f32_e32 v21, 1.0, v29
	v_rcp_f32_e32 v89, v21
	v_pk_mul_f32 v[64:65], v[100:101], v[102:103]
	v_pk_mul_f32 v[66:67], v[68:69], v[104:105]
	v_pk_mul_f32 v[68:69], v[70:71], v[86:87]
	v_pk_mul_f32 v[70:71], v[84:85], v[88:89]
	v_mbcnt_hi_u32_b32 v25, -1, v81
	s_cbranch_scc1 .LBB0_384
	v_pk_mul_f32 v[84:85], v[64:65], v[64:65]
	v_pk_mul_f32 v[86:87], v[66:67], v[66:67]
	v_add_f32_e32 v21, v84, v85
	v_add_f32_e32 v21, v86, v21
	v_pk_mul_f32 v[88:89], v[68:69], v[68:69]
	v_add_f32_e32 v21, v87, v21
	v_add_f32_e32 v21, v88, v21
	v_pk_mul_f32 v[90:91], v[70:71], v[70:71]
	v_add_f32_e32 v21, v89, v21
	v_add_f32_e32 v21, v90, v21
	v_add_f32_e32 v21, v91, v21
	s_nop 1
	v_add_f32_dpp v21, v21, v21 quad_perm:[1,0,3,2] row_mask:0xf bank_mask:0xf
	s_nop 1
	v_add_f32_dpp v21, v21, v21 quad_perm:[2,3,0,1] row_mask:0xf bank_mask:0xf
	s_nop 1
	v_add_f32_dpp v21, v21, v21 row_half_mirror row_mask:0xf bank_mask:0xf
	s_nop 1
	v_add_f32_dpp v21, v21, v21 row_mirror row_mask:0xf bank_mask:0xf
	v_add_f32_e32 v21, 0x358637bd, v21
	v_mul_f32_e32 v29, 0x4b800000, v21
	v_cmp_gt_f32_e32 vcc, s42, v21
	s_nop 1
	v_cndmask_b32_e32 v21, v21, v29, vcc
	v_rsq_f32_e32 v21, v21
	s_nop 0
	v_mul_f32_e32 v29, 0x45800000, v21
	v_cndmask_b32_e32 v21, v21, v29, vcc
	v_mul_f32_e32 v84, v82, v21
	v_pk_mul_f32 v[70:71], v[70:71], v[84:85] op_sel_hi:[1,0]
	v_pk_mul_f32 v[68:69], v[68:69], v[84:85] op_sel_hi:[1,0]
	v_pk_mul_f32 v[66:67], v[66:67], v[84:85] op_sel_hi:[1,0]
	v_pk_mul_f32 v[64:65], v[64:65], v[84:85] op_sel_hi:[1,0]
; #define LAS __attribute__((address_space(3)))
; __device__ __forceinline__ vu4 pack8(const float (&f)[8]) { vu4 w; w.x = pg8::cvt_pk_bf16(f[0], f[1]); w.y = pg8::cvt_pk_bf16(f[2], f[3]); w.z = pg8::cvt_pk_bf16(f[4], f[5]); w.w = pg8::cvt_pk_bf16(f[6], f[7]); return w; }
; __device__ __forceinline__ float silu_f(float x) { return x * __builtin_amdgcn_rcpf(1.0f + __expf(-x)); }
; __device__ __forceinline__ void ph_conv_inplace(lds_u8* lds, bf16_t* XT, const float* convw, const bf16_t* halo, int norm_mode) {
;     ...
;         for (int i = 0; i < 2; ++i) { const int r = (tid >> 4) + 32 * i; float acc[8];
; #pragma unroll
;             for (int j = 0; j < 8; ++j) acc[j] = 0.f;
; #pragma unroll
;             for (int tap = 0; tap < 5; ++tap) { float xv[8]; unpack8(*(const LAS vu4*)(raw + (r + tap) * 128 + g8 * 8), xv);
; #pragma unroll
;                 for (int j = 0; j < 8; ++j) acc[j] += cw[tap][j] * xv[j]; }
;             float ss = 0.f;
; #pragma unroll
;             for (int j = 0; j < 8; ++j) { acc[j] = silu_f(acc[j]); ss += acc[j] * acc[j]; }
;             if (norm_mode == 1 && cb < 32) { ss += __shfl_xor(ss, 1); ss += __shfl_xor(ss, 2); ss += __shfl_xor(ss, 4); ss += __shfl_xor(ss, 8);
;                 const float sc = rsqrtf(ss + EPSN) * (cb < 16 ? 0.08838834764831845f : 1.0f);
; #pragma unroll
;                 for (int j = 0; j < 8; ++j) acc[j] *= sc; }
;             outv[i] = pack8(acc); }
.LBB0_384:
	ds_read_b128 v[84:87], v77 offset:8448
	ds_read_b128 v[88:91], v77 offset:8704
	ds_read_b128 v[92:95], v77 offset:8192
	ds_read_b128 v[96:99], v77 offset:8960
	ds_read_b128 v[100:103], v77 offset:9216
	s_waitcnt lgkmcnt(4)
	v_lshlrev_b32_e32 v21, 16, v87
	s_waitcnt lgkmcnt(3)
	v_lshlrev_b32_e32 v29, 16, v91
	s_waitcnt lgkmcnt(2)
	v_lshlrev_b32_e32 v108, 16, v92
	v_and_b32_e32 v109, 0xffff0000, v92
	v_pk_fma_f32 v[34:35], v[34:35], v[108:109], 0 op_sel_hi:[1,1,0]
	v_lshlrev_b32_e32 v108, 16, v84
	v_and_b32_e32 v109, 0xffff0000, v84
	v_pk_fma_f32 v[34:35], v[38:39], v[108:109], v[34:35]
	v_lshlrev_b32_e32 v38, 16, v88
	v_and_b32_e32 v39, 0xffff0000, v88
	v_pk_fma_f32 v[34:35], v[42:43], v[38:39], v[34:35]
	s_waitcnt lgkmcnt(1)
	v_lshlrev_b32_e32 v38, 16, v96
	v_and_b32_e32 v39, 0xffff0000, v96
	v_pk_fma_f32 v[34:35], v[50:51], v[38:39], v[34:35]
	s_waitcnt lgkmcnt(0)
	v_lshlrev_b32_e32 v38, 16, v100
	v_and_b32_e32 v39, 0xffff0000, v100
	v_lshlrev_b32_e32 v42, 16, v93
	v_and_b32_e32 v43, 0xffff0000, v93
	v_pk_fma_f32 v[34:35], v[46:47], v[38:39], v[34:35]
	v_pk_fma_f32 v[36:37], v[36:37], v[42:43], 0 op_sel_hi:[1,1,0]
	v_lshlrev_b32_e32 v42, 16, v85
	v_and_b32_e32 v43, 0xffff0000, v85
	v_mul_f32_e32 v106, v24, v29
	v_mul_f32_e32 v24, 0xbfb8aa3b, v34
	v_pk_fma_f32 v[36:37], v[40:41], v[42:43], v[36:37]
	v_lshlrev_b32_e32 v40, 16, v89
	v_and_b32_e32 v41, 0xffff0000, v89
	v_mul_f32_e32 v104, v20, v21
	v_and_b32_e32 v21, 0xffff0000, v91
	v_and_b32_e32 v20, 0xffff0000, v87
	v_exp_f32_e32 v24, v24
	v_mul_f32_e32 v29, 0xbfb8aa3b, v35
	v_pk_fma_f32 v[36:37], v[44:45], v[40:41], v[36:37]
	v_lshlrev_b32_e32 v40, 16, v97
	v_and_b32_e32 v41, 0xffff0000, v97
	v_pk_mul_f32 v[74:75], v[74:75], v[20:21]
	v_lshlrev_b32_e32 v20, 16, v99
	v_exp_f32_e32 v29, v29
	v_pk_fma_f32 v[36:37], v[52:53], v[40:41], v[36:37]
	v_lshlrev_b32_e32 v40, 16, v101
	v_and_b32_e32 v41, 0xffff0000, v101
	v_mul_f32_e32 v28, v28, v20
	v_lshlrev_b32_e32 v20, 16, v103
	v_pk_fma_f32 v[36:37], v[48:49], v[40:41], v[36:37]
	v_lshlrev_b32_e32 v40, 16, v94
	v_and_b32_e32 v41, 0xffff0000, v94
	v_mul_f32_e32 v32, v32, v20
	v_and_b32_e32 v21, 0xffff0000, v103
	v_and_b32_e32 v20, 0xffff0000, v99
	v_pk_fma_f32 v[14:15], v[14:15], v[40:41], 0 op_sel_hi:[1,1,0]
	v_lshlrev_b32_e32 v40, 16, v86
	v_and_b32_e32 v41, 0xffff0000, v86
	v_pk_mul_f32 v[38:39], v[72:73], v[20:21]
	v_add_f32_e32 v20, 1.0, v24
	v_mul_f32_e32 v24, 0xbfb8aa3b, v36
	v_pk_fma_f32 v[14:15], v[18:19], v[40:41], v[14:15]
	v_lshlrev_b32_e32 v18, 16, v90
	v_and_b32_e32 v19, 0xffff0000, v90
	v_add_f32_e32 v21, 1.0, v29
	v_exp_f32_e32 v24, v24
	v_mul_f32_e32 v29, 0xbfb8aa3b, v37
	v_pk_fma_f32 v[14:15], v[22:23], v[18:19], v[14:15]
	v_lshlrev_b32_e32 v18, 16, v98
	v_and_b32_e32 v19, 0xffff0000, v98
	v_rcp_f32_e32 v20, v20
	v_rcp_f32_e32 v21, v21
	v_exp_f32_e32 v29, v29
	v_pk_fma_f32 v[14:15], v[26:27], v[18:19], v[14:15]
	v_lshlrev_b32_e32 v18, 16, v102
	v_and_b32_e32 v19, 0xffff0000, v102
	v_pk_fma_f32 v[18:19], v[30:31], v[18:19], v[14:15]
	v_and_b32_e32 v27, 0xffff0000, v95
	v_lshlrev_b32_e32 v26, 16, v95
	v_mul_f32_e32 v14, 0xbfb8aa3b, v18
	v_pk_fma_f32 v[16:17], v[16:17], v[26:27], 0 op_sel_hi:[1,1,0]
	v_mov_b32_e32 v105, v74
	v_add_f32_e32 v24, 1.0, v24
	v_exp_f32_e32 v22, v14
	v_mul_f32_e32 v14, 0xbfb8aa3b, v19
	v_pk_add_f32 v[16:17], v[16:17], v[104:105]
	v_mov_b32_e32 v107, v75
	v_pk_mul_f32 v[20:21], v[34:35], v[20:21]
	v_rcp_f32_e32 v34, v24
	v_add_f32_e32 v24, 1.0, v29
	v_exp_f32_e32 v23, v14
	v_pk_add_f32 v[16:17], v[16:17], v[106:107]
	v_mov_b32_e32 v29, v38
	v_pk_add_f32 v[16:17], v[16:17], v[28:29]
	v_mov_b32_e32 v33, v39
	v_pk_add_f32 v[26:27], v[16:17], v[32:33]
	v_rcp_f32_e32 v35, v24
	v_mul_f32_e32 v16, 0xbfb8aa3b, v26
	v_add_f32_e32 v22, 1.0, v22
	v_add_f32_e32 v23, 1.0, v23
	v_exp_f32_e32 v24, v16
	v_mul_f32_e32 v16, 0xbfb8aa3b, v27
	v_rcp_f32_e32 v22, v22
	v_rcp_f32_e32 v23, v23
	v_exp_f32_e32 v28, v16
	v_pk_mul_f32 v[14:15], v[36:37], v[34:35]
	s_andn2_b64 vcc, exec, s[20:21]
	v_pk_mul_f32 v[16:17], v[18:19], v[22:23]
	v_add_f32_e32 v18, 1.0, v24
	v_add_f32_e32 v19, 1.0, v28
	v_rcp_f32_e32 v18, v18
	v_rcp_f32_e32 v19, v19
	s_nop 0
	v_pk_mul_f32 v[18:19], v[26:27], v[18:19]
	s_cbranch_vccnz .LBB0_365
	v_pk_mul_f32 v[22:23], v[20:21], v[20:21]
	v_pk_mul_f32 v[26:27], v[14:15], v[14:15]
	v_add_f32_e32 v22, v22, v23
	v_add_f32_e32 v22, v26, v22
	v_pk_mul_f32 v[28:29], v[16:17], v[16:17]
	v_add_f32_e32 v22, v27, v22
	v_add_f32_e32 v22, v28, v22
	v_pk_mul_f32 v[30:31], v[18:19], v[18:19]
	v_add_f32_e32 v22, v29, v22
	v_add_f32_e32 v22, v30, v22
	v_add_f32_e32 v22, v31, v22
	s_nop 1
	v_add_f32_dpp v22, v22, v22 quad_perm:[1,0,3,2] row_mask:0xf bank_mask:0xf
	s_nop 1
	v_add_f32_dpp v22, v22, v22 quad_perm:[2,3,0,1] row_mask:0xf bank_mask:0xf
	s_nop 1
	v_add_f32_dpp v22, v22, v22 row_half_mirror row_mask:0xf bank_mask:0xf
	s_nop 1
	v_add_f32_dpp v22, v22, v22 row_mirror row_mask:0xf bank_mask:0xf
	v_add_f32_e32 v22, 0x358637bd, v22
	v_mul_f32_e32 v23, 0x4b800000, v22
	v_cmp_gt_f32_e32 vcc, s42, v22
	s_nop 1
	v_cndmask_b32_e32 v22, v22, v23, vcc
	v_rsq_f32_e32 v22, v22
	s_nop 0
	v_mul_f32_e32 v23, 0x45800000, v22
	v_cndmask_b32_e32 v22, v22, v23, vcc
	v_mul_f32_e32 v22, v82, v22
	v_pk_mul_f32 v[18:19], v[18:19], v[22:23] op_sel_hi:[1,0]
	v_pk_mul_f32 v[16:17], v[16:17], v[22:23] op_sel_hi:[1,0]
	v_pk_mul_f32 v[14:15], v[14:15], v[22:23] op_sel_hi:[1,0]
	v_pk_mul_f32 v[20:21], v[20:21], v[22:23] op_sel_hi:[1,0]
	s_branch .LBB0_365
